# v94 + the control words are zeroed and published by the last workgroup (one P0 unit fewer than workgroups 0..15) instead of workgroup 0
# baseline (speedup 1.0000x reference)
; #define PG8_LAS __attribute__((address_space(3)))
; #define LAS __attribute__((address_space(3)))
; #define KP (kparams())
; __global__ void __launch_bounds__(512) fwd_kernel(Params p_unused) {
;     ...
;     const int G = gridDim.x, bid = blockIdx.x;
;     unsigned char* ws = KP.ws;
;     PG8_LAS unsigned char* lds3 = (PG8_LAS unsigned char*)smem;
;     unsigned* barw = (unsigned*)(ws + WS_BAR);
;     volatile LAS unsigned* xst = (volatile LAS unsigned*)(lds3 + (LDS_BYTES - 64));
;     if (bid == 0) for (int i = threadIdx.x; i < CTL_WORDS; i += 512) barw[i] = 0u;
;     if (threadIdx.x < 4) xst[threadIdx.x] = 0u;
_Z10fwd_kernel6Params:
	s_load_dwordx2 s[92:93], s[0:1], 0xc0
	s_load_dword s3, s[0:1], 0xc8
	s_mov_b64 s[4:5], s[0:1]
	s_load_dwordx2 s[82:83], s[4:5], 0xb8
	s_add_u32 s42, s0, 0xc0
	s_waitcnt lgkmcnt(0)
	v_writelane_b32 v252, s3, 0
	v_writelane_b32 v252, s0, 1
	s_addc_u32 s43, s1, 0
	s_add_u32 s84, s82, 0x38a00000
	s_addc_u32 s85, s83, 0
	s_add_i32 s3, s92, -1
	s_cmp_lg_u32 s2, s3
	v_and_b32_e32 v172, 0x3ff, v0
	v_writelane_b32 v252, s1, 2
	s_cbranch_scc0 .LBB0_189
	v_cmp_gt_u32_e32 vcc, 4, v172
	v_lshl_add_u32 v173, v172, 2, 0
	s_and_saveexec_b64 s[4:5], vcc
